# V^T epilogue: rs-row loads of the four token groups issued ahead into spare VGPRs (one exposed round trip instead of four)
# speedup vs baseline: 1.0061x; 1.0061x over previous
.LBB0_216:
	v_lshl_or_b32 v162, s58, 8, v181
	v_ashrrev_i32_e32 v163, 31, v162
	v_lshl_add_u64 v[144:145], v[162:163], 4, s[6:7]
	v_mov_b64_e32 v[250:251], v[144:145]
	global_load_dwordx4 v[132:135], v[144:145], off offset:48
	global_load_dwordx4 v[136:139], v[144:145], off offset:32
	global_load_dwordx4 v[140:143], v[144:145], off offset:16
	s_nop 0
	global_load_dwordx4 v[144:147], v[144:145], off
	global_load_dwordx4 v[186:189], v[250:251], off offset:112
	global_load_dwordx4 v[190:193], v[250:251], off offset:96
	global_load_dwordx4 v[194:197], v[250:251], off offset:80
	global_load_dwordx4 v[198:201], v[250:251], off offset:64
	global_load_dwordx4 v[202:205], v[250:251], off offset:2096
	global_load_dwordx4 v[206:209], v[250:251], off offset:2080
	global_load_dwordx4 v[210:213], v[250:251], off offset:2064
	global_load_dwordx4 v[234:237], v[250:251], off offset:2048
	s_mov_b32 s14, 0xf800000
	s_waitcnt vmcnt(8)
	v_mov_b32_e32 v158, v145
	v_mov_b32_e32 v159, v146
	v_mov_b32_e32 v145, v147
	v_pk_add_f32 v[144:145], v[158:159], v[144:145]
	s_nop 0
	v_add_f32_e32 v144, v144, v145
	v_fmamk_f32 v144, v144, 0x3a800000, v215
	v_cmp_gt_f32_e32 vcc, s14, v144
	v_mul_f32_e32 v145, 0x4f800000, v144
	s_nop 0
	v_cndmask_b32_e32 v144, v144, v145, vcc
	v_sqrt_f32_e32 v145, v144
	s_nop 0
	v_add_u32_e32 v146, -1, v145
	v_fma_f32 v147, -v146, v145, v144
	v_cmp_ge_f32_e64 s[4:5], 0, v147
	v_add_u32_e32 v147, 1, v145
	s_nop 0
	v_cndmask_b32_e64 v146, v145, v146, s[4:5]
	v_fma_f32 v145, -v147, v145, v144
	v_cmp_lt_f32_e64 s[4:5], 0, v145
	s_nop 1
	v_cndmask_b32_e64 v145, v146, v147, s[4:5]
	v_mul_f32_e32 v146, 0x37800000, v145
	v_cndmask_b32_e32 v145, v145, v146, vcc
	v_cmp_class_f32_e32 vcc, v144, v216
	s_nop 1
	v_cndmask_b32_e32 v144, v145, v144, vcc
	v_div_scale_f32 v145, s[4:5], v144, v144, 1.0
	v_rcp_f32_e32 v146, v145
	s_nop 0
	v_fma_f32 v147, -v145, v146, 1.0
	v_fmac_f32_e32 v146, v147, v146
	v_div_scale_f32 v147, vcc, 1.0, v144, 1.0
	v_mul_f32_e32 v158, v147, v146
	v_fma_f32 v159, -v145, v158, v147
	v_fmac_f32_e32 v158, v159, v146
	v_fma_f32 v145, -v145, v158, v147
	v_div_fmas_f32 v145, v145, v146, v158
	v_div_fixup_f32 v158, v145, v144, 1.0
	v_mov_b32_e32 v144, v141
	v_mov_b32_e32 v145, v142
	v_mov_b32_e32 v141, v143
	v_pk_add_f32 v[140:141], v[144:145], v[140:141]
	s_nop 0
	v_add_f32_e32 v140, v140, v141
	v_fmamk_f32 v140, v140, 0x3a800000, v215
	v_cmp_gt_f32_e32 vcc, s14, v140
	v_mul_f32_e32 v141, 0x4f800000, v140
	s_nop 0
	v_cndmask_b32_e32 v140, v140, v141, vcc
	v_sqrt_f32_e32 v141, v140
	s_nop 0
	v_add_u32_e32 v142, -1, v141
	v_fma_f32 v143, -v142, v141, v140
	v_cmp_ge_f32_e64 s[4:5], 0, v143
	v_add_u32_e32 v143, 1, v141
	s_nop 0
	v_cndmask_b32_e64 v142, v141, v142, s[4:5]
	v_fma_f32 v141, -v143, v141, v140
	v_cmp_lt_f32_e64 s[4:5], 0, v141
	s_nop 1
	v_cndmask_b32_e64 v141, v142, v143, s[4:5]
	v_mul_f32_e32 v142, 0x37800000, v141
	v_cndmask_b32_e32 v141, v141, v142, vcc
	v_cmp_class_f32_e32 vcc, v140, v216
	s_nop 1
	v_cndmask_b32_e32 v140, v141, v140, vcc
	v_div_scale_f32 v141, s[4:5], v140, v140, 1.0
	v_rcp_f32_e32 v142, v141
	s_nop 0
	v_fma_f32 v143, -v141, v142, 1.0
	v_fmac_f32_e32 v142, v143, v142
	v_div_scale_f32 v143, vcc, 1.0, v140, 1.0
	v_mul_f32_e32 v144, v143, v142
	v_fma_f32 v145, -v141, v144, v143
	v_fmac_f32_e32 v144, v145, v142
	v_fma_f32 v141, -v141, v144, v143
	v_div_fmas_f32 v141, v141, v142, v144
	v_div_fixup_f32 v159, v141, v140, 1.0
	v_mov_b32_e32 v140, v137
	v_mov_b32_e32 v141, v138
	v_mov_b32_e32 v137, v139
	v_pk_add_f32 v[136:137], v[140:141], v[136:137]
	v_pk_mul_f32 v[128:129], v[128:129], v[158:159]
	v_add_f32_e32 v136, v136, v137
	v_fmamk_f32 v136, v136, 0x3a800000, v215
	v_cmp_gt_f32_e32 vcc, s14, v136
	v_mul_f32_e32 v137, 0x4f800000, v136
	v_pk_mul_f32 v[116:117], v[116:117], v[158:159]
	v_cndmask_b32_e32 v136, v136, v137, vcc
	v_sqrt_f32_e32 v137, v136
	v_pk_mul_f32 v[100:101], v[100:101], v[158:159]
	v_pk_mul_f32 v[84:85], v[84:85], v[158:159]
	v_pk_mul_f32 v[64:65], v[64:65], v[158:159]
	v_add_u32_e32 v138, -1, v137
	v_fma_f32 v139, -v138, v137, v136
	v_cmp_ge_f32_e64 s[4:5], 0, v139
	v_add_u32_e32 v139, 1, v137
	v_pk_mul_f32 v[52:53], v[52:53], v[158:159]
	v_cndmask_b32_e64 v138, v137, v138, s[4:5]
	v_fma_f32 v137, -v139, v137, v136
	v_cmp_lt_f32_e64 s[4:5], 0, v137
	v_pk_mul_f32 v[36:37], v[36:37], v[158:159]
	v_pk_mul_f32 v[20:21], v[20:21], v[158:159]
	v_cndmask_b32_e64 v137, v138, v139, s[4:5]
	v_mul_f32_e32 v138, 0x37800000, v137
	v_cndmask_b32_e32 v137, v137, v138, vcc
	v_cmp_class_f32_e32 vcc, v136, v216
	s_nop 1
	v_cndmask_b32_e32 v136, v137, v136, vcc
	v_div_scale_f32 v137, s[4:5], v136, v136, 1.0
	v_rcp_f32_e32 v138, v137
	s_nop 0
	v_fma_f32 v139, -v137, v138, 1.0
	v_fmac_f32_e32 v138, v139, v138
	v_div_scale_f32 v139, vcc, 1.0, v136, 1.0
	v_mul_f32_e32 v140, v139, v138
	v_fma_f32 v141, -v137, v140, v139
	v_fmac_f32_e32 v140, v141, v138
	v_fma_f32 v137, -v137, v140, v139
	v_div_fmas_f32 v137, v137, v138, v140
	v_div_fixup_f32 v160, v137, v136, 1.0
	v_mov_b32_e32 v136, v133
	v_mov_b32_e32 v137, v134
	v_mov_b32_e32 v133, v135
	v_pk_add_f32 v[132:133], v[136:137], v[132:133]
	s_nop 0
	v_add_f32_e32 v132, v132, v133
	v_fmamk_f32 v132, v132, 0x3a800000, v215
	v_cmp_gt_f32_e32 vcc, s14, v132
	v_mul_f32_e32 v133, 0x4f800000, v132
	s_nop 0
	v_cndmask_b32_e32 v132, v132, v133, vcc
	v_sqrt_f32_e32 v133, v132
	s_nop 0
	v_add_u32_e32 v134, -1, v133
	v_fma_f32 v135, -v134, v133, v132
	v_cmp_ge_f32_e64 s[4:5], 0, v135
	v_add_u32_e32 v135, 1, v133
	s_nop 0
	v_cndmask_b32_e64 v134, v133, v134, s[4:5]
	v_fma_f32 v133, -v135, v133, v132
	v_cmp_lt_f32_e64 s[4:5], 0, v133
	s_nop 1
	v_cndmask_b32_e64 v133, v134, v135, s[4:5]
	v_mul_f32_e32 v134, 0x37800000, v133
	v_cndmask_b32_e32 v133, v133, v134, vcc
	v_cmp_class_f32_e32 vcc, v132, v216
	s_nop 1
	v_cndmask_b32_e32 v132, v133, v132, vcc
	v_div_scale_f32 v133, s[4:5], v132, v132, 1.0
	v_rcp_f32_e32 v134, v133
	s_nop 0
	v_fma_f32 v135, -v133, v134, 1.0
	v_fmac_f32_e32 v134, v135, v134
	v_div_scale_f32 v135, vcc, 1.0, v132, 1.0
	v_mul_f32_e32 v136, v135, v134
	v_fma_f32 v137, -v133, v136, v135
	v_fmac_f32_e32 v136, v137, v134
	v_fma_f32 v133, -v133, v136, v135
	v_div_fmas_f32 v133, v133, v134, v136
	v_div_fixup_f32 v161, v133, v132, 1.0
	v_pk_mul_f32 v[130:131], v[130:131], v[160:161]
	v_pk_mul_f32 v[66:67], v[66:67], v[160:161]
	s_waitcnt vmcnt(4)
	v_mov_b64_e32 v[132:133], v[186:187]
	v_mov_b64_e32 v[134:135], v[188:189]
	v_mov_b64_e32 v[136:137], v[190:191]
	v_mov_b64_e32 v[138:139], v[192:193]
	v_mov_b64_e32 v[140:141], v[194:195]
	v_mov_b64_e32 v[142:143], v[196:197]
	v_mov_b64_e32 v[144:145], v[198:199]
	v_mov_b64_e32 v[146:147], v[200:201]
	global_load_dwordx4 v[186:189], v[250:251], off offset:2160
	global_load_dwordx4 v[190:193], v[250:251], off offset:2144
	global_load_dwordx4 v[194:197], v[250:251], off offset:2128
	global_load_dwordx4 v[198:201], v[250:251], off offset:2112
	v_mov_b32_e32 v164, v145
	v_mov_b32_e32 v165, v146
	v_mov_b32_e32 v145, v147
	v_pk_add_f32 v[144:145], v[164:165], v[144:145]
	s_nop 0
	v_add_f32_e32 v144, v144, v145
	v_fmamk_f32 v144, v144, 0x3a800000, v215
	v_cmp_gt_f32_e32 vcc, s14, v144
	v_mul_f32_e32 v145, 0x4f800000, v144
	s_nop 0
	v_cndmask_b32_e32 v144, v144, v145, vcc
	v_sqrt_f32_e32 v145, v144
	s_nop 0
	v_add_u32_e32 v146, -1, v145
	v_fma_f32 v147, -v146, v145, v144
	v_cmp_ge_f32_e64 s[4:5], 0, v147
	v_add_u32_e32 v147, 1, v145
	s_nop 0
	v_cndmask_b32_e64 v146, v145, v146, s[4:5]
	v_fma_f32 v145, -v147, v145, v144
	v_cmp_lt_f32_e64 s[4:5], 0, v145
	s_nop 1
	v_cndmask_b32_e64 v145, v146, v147, s[4:5]
	v_mul_f32_e32 v146, 0x37800000, v145
	v_cndmask_b32_e32 v145, v145, v146, vcc
	v_cmp_class_f32_e32 vcc, v144, v216
	s_nop 1
	v_cndmask_b32_e32 v144, v145, v144, vcc
	v_div_scale_f32 v145, s[4:5], v144, v144, 1.0
	v_rcp_f32_e32 v146, v145
	s_nop 0
	v_fma_f32 v147, -v145, v146, 1.0
	v_fmac_f32_e32 v146, v147, v146
	v_div_scale_f32 v147, vcc, 1.0, v144, 1.0
	v_mul_f32_e32 v164, v147, v146
	v_fma_f32 v165, -v145, v164, v147
	v_fmac_f32_e32 v164, v165, v146
	v_fma_f32 v145, -v145, v164, v147
	v_div_fmas_f32 v145, v145, v146, v164
	v_div_fixup_f32 v164, v145, v144, 1.0
	v_mov_b32_e32 v144, v141
	v_mov_b32_e32 v145, v142
	v_mov_b32_e32 v141, v143
	v_pk_add_f32 v[140:141], v[144:145], v[140:141]
	s_nop 0
	v_add_f32_e32 v140, v140, v141
	v_fmamk_f32 v140, v140, 0x3a800000, v215
	v_cmp_gt_f32_e32 vcc, s14, v140
	v_mul_f32_e32 v141, 0x4f800000, v140
	s_nop 0
	v_cndmask_b32_e32 v140, v140, v141, vcc
	v_sqrt_f32_e32 v141, v140
	s_nop 0
	v_add_u32_e32 v142, -1, v141
	v_fma_f32 v143, -v142, v141, v140
	v_cmp_ge_f32_e64 s[4:5], 0, v143
	v_add_u32_e32 v143, 1, v141
	s_nop 0
	v_cndmask_b32_e64 v142, v141, v142, s[4:5]
	v_fma_f32 v141, -v143, v141, v140
	v_cmp_lt_f32_e64 s[4:5], 0, v141
	s_nop 1
	v_cndmask_b32_e64 v141, v142, v143, s[4:5]
	v_mul_f32_e32 v142, 0x37800000, v141
	v_cndmask_b32_e32 v141, v141, v142, vcc
	v_cmp_class_f32_e32 vcc, v140, v216
	s_nop 1
	v_cndmask_b32_e32 v140, v141, v140, vcc
	v_div_scale_f32 v141, s[4:5], v140, v140, 1.0
	v_rcp_f32_e32 v142, v141
	s_nop 0
	v_fma_f32 v143, -v141, v142, 1.0
	v_fmac_f32_e32 v142, v143, v142
	v_div_scale_f32 v143, vcc, 1.0, v140, 1.0
	v_mul_f32_e32 v144, v143, v142
	v_fma_f32 v145, -v141, v144, v143
	v_fmac_f32_e32 v144, v145, v142
	v_fma_f32 v141, -v141, v144, v143
	v_div_fmas_f32 v141, v141, v142, v144
	v_div_fixup_f32 v165, v141, v140, 1.0
	v_mov_b32_e32 v140, v137
	v_mov_b32_e32 v141, v138
	v_mov_b32_e32 v137, v139
	v_pk_add_f32 v[136:137], v[140:141], v[136:137]
	s_nop 0
	v_add_f32_e32 v136, v136, v137
	v_fmamk_f32 v136, v136, 0x3a800000, v215
	v_cmp_gt_f32_e32 vcc, s14, v136
	v_mul_f32_e32 v137, 0x4f800000, v136
	s_nop 0
	v_cndmask_b32_e32 v136, v136, v137, vcc
	v_sqrt_f32_e32 v137, v136
	s_nop 0
	v_add_u32_e32 v138, -1, v137
	v_fma_f32 v139, -v138, v137, v136
	v_cmp_ge_f32_e64 s[4:5], 0, v139
	v_add_u32_e32 v139, 1, v137
	s_nop 0
	v_cndmask_b32_e64 v138, v137, v138, s[4:5]
	v_fma_f32 v137, -v139, v137, v136
	v_cmp_lt_f32_e64 s[4:5], 0, v137
	s_nop 1
	v_cndmask_b32_e64 v137, v138, v139, s[4:5]
	v_mul_f32_e32 v138, 0x37800000, v137
	v_cndmask_b32_e32 v137, v137, v138, vcc
	v_cmp_class_f32_e32 vcc, v136, v216
	s_nop 1
	v_cndmask_b32_e32 v136, v137, v136, vcc
	v_div_scale_f32 v137, s[4:5], v136, v136, 1.0
	v_rcp_f32_e32 v138, v137
	s_nop 0
	v_fma_f32 v139, -v137, v138, 1.0
	v_fmac_f32_e32 v138, v139, v138
	v_div_scale_f32 v139, vcc, 1.0, v136, 1.0
	v_mul_f32_e32 v140, v139, v138
	v_fma_f32 v141, -v137, v140, v139
	v_fmac_f32_e32 v140, v141, v138
	v_fma_f32 v137, -v137, v140, v139
	v_div_fmas_f32 v137, v137, v138, v140
	v_div_fixup_f32 v166, v137, v136, 1.0
	v_mov_b32_e32 v136, v133
	v_mov_b32_e32 v137, v134
	v_mov_b32_e32 v133, v135
	v_pk_add_f32 v[132:133], v[136:137], v[132:133]
	s_nop 0
	v_add_f32_e32 v132, v132, v133
	v_fmamk_f32 v132, v132, 0x3a800000, v215
	v_cmp_gt_f32_e32 vcc, s14, v132
	v_mul_f32_e32 v133, 0x4f800000, v132
	s_nop 0
	v_cndmask_b32_e32 v132, v132, v133, vcc
	v_sqrt_f32_e32 v133, v132
	s_nop 0
	v_add_u32_e32 v134, -1, v133
	v_fma_f32 v135, -v134, v133, v132
	v_cmp_ge_f32_e64 s[4:5], 0, v135
	v_add_u32_e32 v135, 1, v133
	s_nop 0
	v_cndmask_b32_e64 v134, v133, v134, s[4:5]
	v_fma_f32 v133, -v135, v133, v132
	v_cmp_lt_f32_e64 s[4:5], 0, v133
	s_nop 1
	v_cndmask_b32_e64 v133, v134, v135, s[4:5]
	v_mul_f32_e32 v134, 0x37800000, v133
	v_cndmask_b32_e32 v133, v133, v134, vcc
	v_cmp_class_f32_e32 vcc, v132, v216
	s_nop 1
	v_cndmask_b32_e32 v132, v133, v132, vcc
	v_div_scale_f32 v133, s[4:5], v132, v132, 1.0
	v_rcp_f32_e32 v134, v133
	s_nop 0
	v_fma_f32 v135, -v133, v134, 1.0
	v_fmac_f32_e32 v134, v135, v134
	v_div_scale_f32 v135, vcc, 1.0, v132, 1.0
	v_mul_f32_e32 v136, v135, v134
	v_fma_f32 v137, -v133, v136, v135
	v_fmac_f32_e32 v136, v137, v134
	v_fma_f32 v133, -v133, v136, v135
	v_div_fmas_f32 v133, v133, v134, v136
	v_div_fixup_f32 v167, v133, v132, 1.0
	s_waitcnt vmcnt(4)
	v_mov_b64_e32 v[132:133], v[202:203]
	v_mov_b64_e32 v[134:135], v[204:205]
	v_mov_b64_e32 v[136:137], v[206:207]
	v_mov_b64_e32 v[138:139], v[208:209]
	v_mov_b64_e32 v[140:141], v[210:211]
	v_mov_b64_e32 v[142:143], v[212:213]
	v_mov_b64_e32 v[144:145], v[234:235]
	v_mov_b64_e32 v[146:147], v[236:237]
	v_mov_b32_e32 v176, v145
	v_mov_b32_e32 v177, v146
	v_mov_b32_e32 v145, v147
	v_pk_add_f32 v[144:145], v[176:177], v[144:145]
	s_nop 0
	v_add_f32_e32 v144, v144, v145
	v_fmamk_f32 v144, v144, 0x3a800000, v215
	v_cmp_gt_f32_e32 vcc, s14, v144
	v_mul_f32_e32 v145, 0x4f800000, v144
	s_nop 0
	v_cndmask_b32_e32 v144, v144, v145, vcc
	v_sqrt_f32_e32 v145, v144
	s_nop 0
	v_add_u32_e32 v146, -1, v145
	v_fma_f32 v147, -v146, v145, v144
	v_cmp_ge_f32_e64 s[4:5], 0, v147
	v_add_u32_e32 v147, 1, v145
	s_nop 0
	v_cndmask_b32_e64 v146, v145, v146, s[4:5]
	v_fma_f32 v145, -v147, v145, v144
	v_cmp_lt_f32_e64 s[4:5], 0, v145
	s_nop 1
	v_cndmask_b32_e64 v145, v146, v147, s[4:5]
	v_mul_f32_e32 v146, 0x37800000, v145
	v_cndmask_b32_e32 v145, v145, v146, vcc
	v_cmp_class_f32_e32 vcc, v144, v216
	s_nop 1
	v_cndmask_b32_e32 v144, v145, v144, vcc
	v_div_scale_f32 v145, s[4:5], v144, v144, 1.0
	v_rcp_f32_e32 v146, v145
	s_nop 0
	v_fma_f32 v147, -v145, v146, 1.0
	v_fmac_f32_e32 v146, v147, v146
	v_div_scale_f32 v147, vcc, 1.0, v144, 1.0
	v_mul_f32_e32 v176, v147, v146
	v_fma_f32 v177, -v145, v176, v147
	v_fmac_f32_e32 v176, v177, v146
	v_fma_f32 v145, -v145, v176, v147
	v_div_fmas_f32 v145, v145, v146, v176
	v_div_fixup_f32 v176, v145, v144, 1.0
	v_mov_b32_e32 v144, v141
	v_mov_b32_e32 v145, v142
	v_mov_b32_e32 v141, v143
	v_pk_add_f32 v[140:141], v[144:145], v[140:141]
	s_nop 0
	v_add_f32_e32 v140, v140, v141
	v_fmamk_f32 v140, v140, 0x3a800000, v215
	v_cmp_gt_f32_e32 vcc, s14, v140
	v_mul_f32_e32 v141, 0x4f800000, v140
	s_nop 0
	v_cndmask_b32_e32 v140, v140, v141, vcc
	v_sqrt_f32_e32 v141, v140
	s_nop 0
	v_add_u32_e32 v142, -1, v141
	v_fma_f32 v143, -v142, v141, v140
	v_cmp_ge_f32_e64 s[4:5], 0, v143
	v_add_u32_e32 v143, 1, v141
	s_nop 0
	v_cndmask_b32_e64 v142, v141, v142, s[4:5]
	v_fma_f32 v141, -v143, v141, v140
	v_cmp_lt_f32_e64 s[4:5], 0, v141
	s_nop 1
	v_cndmask_b32_e64 v141, v142, v143, s[4:5]
	v_mul_f32_e32 v142, 0x37800000, v141
	v_cndmask_b32_e32 v141, v141, v142, vcc
	v_cmp_class_f32_e32 vcc, v140, v216
	s_nop 1
	v_cndmask_b32_e32 v140, v141, v140, vcc
	v_div_scale_f32 v141, s[4:5], v140, v140, 1.0
	v_rcp_f32_e32 v142, v141
	s_nop 0
	v_fma_f32 v143, -v141, v142, 1.0
	v_fmac_f32_e32 v142, v143, v142
	v_div_scale_f32 v143, vcc, 1.0, v140, 1.0
	v_mul_f32_e32 v144, v143, v142
	v_fma_f32 v145, -v141, v144, v143
	v_fmac_f32_e32 v144, v145, v142
	v_fma_f32 v141, -v141, v144, v143
	v_div_fmas_f32 v141, v141, v142, v144
	v_div_fixup_f32 v177, v141, v140, 1.0
	v_mov_b32_e32 v140, v137
	v_mov_b32_e32 v141, v138
	v_mov_b32_e32 v137, v139
	v_pk_add_f32 v[136:137], v[140:141], v[136:137]
	v_pk_mul_f32 v[120:121], v[120:121], v[176:177]
	v_add_f32_e32 v136, v136, v137
	v_fmamk_f32 v136, v136, 0x3a800000, v215
	v_cmp_gt_f32_e32 vcc, s14, v136
	v_mul_f32_e32 v137, 0x4f800000, v136
	v_pk_mul_f32 v[104:105], v[104:105], v[176:177]
	v_cndmask_b32_e32 v136, v136, v137, vcc
	v_sqrt_f32_e32 v137, v136
	v_pk_mul_f32 v[88:89], v[88:89], v[176:177]
	v_pk_mul_f32 v[72:73], v[72:73], v[176:177]
	v_pk_mul_f32 v[56:57], v[56:57], v[176:177]
	v_add_u32_e32 v138, -1, v137
	v_fma_f32 v139, -v138, v137, v136
	v_cmp_ge_f32_e64 s[4:5], 0, v139
	v_add_u32_e32 v139, 1, v137
	v_pk_mul_f32 v[40:41], v[40:41], v[176:177]
	v_cndmask_b32_e64 v138, v137, v138, s[4:5]
	v_fma_f32 v137, -v139, v137, v136
	v_cmp_lt_f32_e64 s[4:5], 0, v137
	v_pk_mul_f32 v[24:25], v[24:25], v[176:177]
	v_pk_mul_f32 v[8:9], v[8:9], v[176:177]
	v_cndmask_b32_e64 v137, v138, v139, s[4:5]
	v_mul_f32_e32 v138, 0x37800000, v137
	v_cndmask_b32_e32 v137, v137, v138, vcc
	v_cmp_class_f32_e32 vcc, v136, v216
	s_nop 1
	v_cndmask_b32_e32 v136, v137, v136, vcc
	v_div_scale_f32 v137, s[4:5], v136, v136, 1.0
	v_rcp_f32_e32 v138, v137
	s_nop 0
	v_fma_f32 v139, -v137, v138, 1.0
	v_fmac_f32_e32 v138, v139, v138
	v_div_scale_f32 v139, vcc, 1.0, v136, 1.0
	v_mul_f32_e32 v140, v139, v138
	v_fma_f32 v141, -v137, v140, v139
	v_fmac_f32_e32 v140, v141, v138
	v_fma_f32 v137, -v137, v140, v139
	v_div_fmas_f32 v137, v137, v138, v140
	v_div_fixup_f32 v178, v137, v136, 1.0
	v_mov_b32_e32 v136, v133
	v_mov_b32_e32 v137, v134
	v_mov_b32_e32 v133, v135
	v_pk_add_f32 v[132:133], v[136:137], v[132:133]
	s_nop 0
	v_add_f32_e32 v132, v132, v133
	v_fmamk_f32 v132, v132, 0x3a800000, v215
	v_cmp_gt_f32_e32 vcc, s14, v132
	v_mul_f32_e32 v133, 0x4f800000, v132
	s_nop 0
	v_cndmask_b32_e32 v132, v132, v133, vcc
	v_sqrt_f32_e32 v133, v132
	s_nop 0
	v_add_u32_e32 v134, -1, v133
	v_fma_f32 v135, -v134, v133, v132
	v_cmp_ge_f32_e64 s[4:5], 0, v135
	v_add_u32_e32 v135, 1, v133
	s_nop 0
	v_cndmask_b32_e64 v134, v133, v134, s[4:5]
	v_fma_f32 v133, -v135, v133, v132
	v_cmp_lt_f32_e64 s[4:5], 0, v133
	s_nop 1
	v_cndmask_b32_e64 v133, v134, v135, s[4:5]
	v_mul_f32_e32 v134, 0x37800000, v133
	v_cndmask_b32_e32 v133, v133, v134, vcc
	v_cmp_class_f32_e32 vcc, v132, v216
	s_nop 1
	v_cndmask_b32_e32 v132, v133, v132, vcc
	v_div_scale_f32 v133, s[4:5], v132, v132, 1.0
	v_rcp_f32_e32 v134, v133
	s_nop 0
	v_fma_f32 v135, -v133, v134, 1.0
	v_fmac_f32_e32 v134, v135, v134
	v_div_scale_f32 v135, vcc, 1.0, v132, 1.0
	v_mul_f32_e32 v136, v135, v134
	v_fma_f32 v137, -v133, v136, v135
	v_fmac_f32_e32 v136, v137, v134
	v_fma_f32 v133, -v133, v136, v135
	v_div_fmas_f32 v133, v133, v134, v136
	v_div_fixup_f32 v179, v133, v132, 1.0
	v_pk_mul_f32 v[122:123], v[122:123], v[178:179]
	v_pk_mul_f32 v[106:107], v[106:107], v[178:179]
	v_pk_mul_f32 v[90:91], v[90:91], v[178:179]
	v_pk_mul_f32 v[74:75], v[74:75], v[178:179]
	v_pk_mul_f32 v[58:59], v[58:59], v[178:179]
	v_pk_mul_f32 v[42:43], v[42:43], v[178:179]
	v_pk_mul_f32 v[26:27], v[26:27], v[178:179]
	v_pk_mul_f32 v[10:11], v[10:11], v[178:179]
	s_waitcnt vmcnt(0)
	v_mov_b64_e32 v[132:133], v[186:187]
	v_mov_b64_e32 v[134:135], v[188:189]
	v_mov_b64_e32 v[136:137], v[190:191]
	v_mov_b64_e32 v[138:139], v[192:193]
	v_mov_b64_e32 v[140:141], v[194:195]
	v_mov_b64_e32 v[142:143], v[196:197]
	v_mov_b64_e32 v[144:145], v[198:199]
	v_mov_b64_e32 v[146:147], v[200:201]
	v_mov_b32_e32 v184, v145
	v_mov_b32_e32 v185, v146
	v_mov_b32_e32 v145, v147
	v_pk_add_f32 v[144:145], v[184:185], v[144:145]
	s_nop 0
	v_add_f32_e32 v144, v144, v145
	v_fmamk_f32 v144, v144, 0x3a800000, v215
	v_cmp_gt_f32_e32 vcc, s14, v144
	v_mul_f32_e32 v145, 0x4f800000, v144
	s_nop 0
	v_cndmask_b32_e32 v144, v144, v145, vcc
	v_sqrt_f32_e32 v145, v144
	s_nop 0
	v_add_u32_e32 v146, -1, v145
	v_fma_f32 v147, -v146, v145, v144
	v_cmp_ge_f32_e64 s[4:5], 0, v147
	v_add_u32_e32 v147, 1, v145
	s_nop 0
	v_cndmask_b32_e64 v146, v145, v146, s[4:5]
	v_fma_f32 v145, -v147, v145, v144
	v_cmp_lt_f32_e64 s[4:5], 0, v145
	s_nop 1
	v_cndmask_b32_e64 v145, v146, v147, s[4:5]
	v_mul_f32_e32 v146, 0x37800000, v145
	v_cndmask_b32_e32 v145, v145, v146, vcc
	v_cmp_class_f32_e32 vcc, v144, v216
	s_nop 1
	v_cndmask_b32_e32 v144, v145, v144, vcc
	v_div_scale_f32 v145, s[4:5], v144, v144, 1.0
	v_rcp_f32_e32 v146, v145
	s_nop 0
	v_fma_f32 v147, -v145, v146, 1.0
	v_fmac_f32_e32 v146, v147, v146
	v_div_scale_f32 v147, vcc, 1.0, v144, 1.0
	v_mul_f32_e32 v183, v147, v146
	v_fma_f32 v184, -v145, v183, v147
	v_fmac_f32_e32 v183, v184, v146
	v_fma_f32 v145, -v145, v183, v147
	v_div_fmas_f32 v145, v145, v146, v183
	v_mov_b32_e32 v146, v141
	v_mov_b32_e32 v147, v142
	v_mov_b32_e32 v141, v143
	v_pk_add_f32 v[140:141], v[146:147], v[140:141]
	v_div_fixup_f32 v144, v145, v144, 1.0
	v_add_f32_e32 v140, v140, v141
	v_fmamk_f32 v140, v140, 0x3a800000, v215
	v_cmp_gt_f32_e32 vcc, s14, v140
	v_mul_f32_e32 v141, 0x4f800000, v140
	s_nop 0
	v_cndmask_b32_e32 v140, v140, v141, vcc
	v_sqrt_f32_e32 v141, v140
	s_nop 0
	v_add_u32_e32 v142, -1, v141
	v_fma_f32 v143, -v142, v141, v140
	v_cmp_ge_f32_e64 s[4:5], 0, v143
	v_add_u32_e32 v143, 1, v141
	s_nop 0
	v_cndmask_b32_e64 v142, v141, v142, s[4:5]
	v_fma_f32 v141, -v143, v141, v140
	v_cmp_lt_f32_e64 s[4:5], 0, v141
	s_nop 1
	v_cndmask_b32_e64 v141, v142, v143, s[4:5]
	v_mul_f32_e32 v142, 0x37800000, v141
	v_cndmask_b32_e32 v141, v141, v142, vcc
	v_cmp_class_f32_e32 vcc, v140, v216
	s_nop 1
	v_cndmask_b32_e32 v140, v141, v140, vcc
	v_div_scale_f32 v141, s[4:5], v140, v140, 1.0
	v_rcp_f32_e32 v142, v141
	s_nop 0
	v_fma_f32 v143, -v141, v142, 1.0
	v_fmac_f32_e32 v142, v143, v142
	v_div_scale_f32 v143, vcc, 1.0, v140, 1.0
	v_mul_f32_e32 v145, v143, v142
	v_fma_f32 v146, -v141, v145, v143
	v_fmac_f32_e32 v145, v146, v142
	v_fma_f32 v141, -v141, v145, v143
	v_div_fmas_f32 v141, v141, v142, v145
	v_div_fixup_f32 v145, v141, v140, 1.0
	v_mov_b32_e32 v140, v137
	v_mov_b32_e32 v141, v138
	v_mov_b32_e32 v137, v139
	v_pk_add_f32 v[136:137], v[140:141], v[136:137]
	s_nop 0
	v_add_f32_e32 v136, v136, v137
	v_fmamk_f32 v136, v136, 0x3a800000, v215
	v_cmp_gt_f32_e32 vcc, s14, v136
	v_mul_f32_e32 v137, 0x4f800000, v136
	s_nop 0
	v_cndmask_b32_e32 v136, v136, v137, vcc
	v_sqrt_f32_e32 v137, v136
	s_nop 0
	v_add_u32_e32 v138, -1, v137
	v_fma_f32 v139, -v138, v137, v136
	v_cmp_ge_f32_e64 s[4:5], 0, v139
	v_add_u32_e32 v139, 1, v137
	s_nop 0
	v_cndmask_b32_e64 v138, v137, v138, s[4:5]
	v_fma_f32 v137, -v139, v137, v136
	v_cmp_lt_f32_e64 s[4:5], 0, v137
	s_nop 1
	v_cndmask_b32_e64 v137, v138, v139, s[4:5]
	v_mul_f32_e32 v138, 0x37800000, v137
	v_cndmask_b32_e32 v137, v137, v138, vcc
	v_cmp_class_f32_e32 vcc, v136, v216
	s_nop 1
	v_cndmask_b32_e32 v136, v137, v136, vcc
	v_div_scale_f32 v137, s[4:5], v136, v136, 1.0
	v_rcp_f32_e32 v138, v137
	s_nop 0
	v_fma_f32 v139, -v137, v138, 1.0
	v_fmac_f32_e32 v138, v139, v138
	v_div_scale_f32 v139, vcc, 1.0, v136, 1.0
	v_mul_f32_e32 v140, v139, v138
	v_fma_f32 v141, -v137, v140, v139
	v_fmac_f32_e32 v140, v141, v138
	v_fma_f32 v137, -v137, v140, v139
	v_div_fmas_f32 v137, v137, v138, v140
	v_mov_b32_e32 v138, v133
	v_mov_b32_e32 v139, v134
	v_mov_b32_e32 v133, v135
	v_pk_add_f32 v[132:133], v[138:139], v[132:133]
	v_div_fixup_f32 v136, v137, v136, 1.0
	v_add_f32_e32 v132, v132, v133
	v_fmamk_f32 v132, v132, 0x3a800000, v215
	v_cmp_gt_f32_e32 vcc, s14, v132
	v_mul_f32_e32 v133, 0x4f800000, v132
	v_pk_mul_f32 v[140:141], v[126:127], v[166:167]
	v_cndmask_b32_e32 v132, v132, v133, vcc
	v_sqrt_f32_e32 v133, v132
	v_pk_mul_f32 v[126:127], v[124:125], v[164:165]
	v_cvt_pk_bf16_f32 v124, v128, v129
	v_cvt_pk_bf16_f32 v125, v130, v131
	v_add_u32_e32 v134, -1, v133
	v_fma_f32 v135, -v134, v133, v132
	v_cmp_ge_f32_e64 s[4:5], 0, v135
	v_add_u32_e32 v135, 1, v133
	v_cvt_pk_bf16_f32 v126, v126, v127
	v_cvt_pk_bf16_f32 v127, v140, v141
	s_nop 0
	v_cndmask_b32_e64 v134, v133, v134, s[4:5]
	v_fma_f32 v133, -v135, v133, v132
	v_cmp_lt_f32_e64 s[4:5], 0, v133
	s_nop 1
	v_cndmask_b32_e64 v133, v134, v135, s[4:5]
	v_mul_f32_e32 v134, 0x37800000, v133
	v_cndmask_b32_e32 v133, v133, v134, vcc
	v_cmp_class_f32_e32 vcc, v132, v216
	s_nop 1
	v_cndmask_b32_e32 v132, v133, v132, vcc
	v_div_scale_f32 v133, s[4:5], v132, v132, 1.0
	v_rcp_f32_e32 v134, v133
	s_mov_b64 s[4:5], 0x400000
	v_fma_f32 v135, -v133, v134, 1.0
	v_fmac_f32_e32 v134, v135, v134
	v_div_scale_f32 v135, vcc, 1.0, v132, 1.0
	v_mul_f32_e32 v137, v135, v134
	v_fma_f32 v138, -v133, v137, v135
	v_fmac_f32_e32 v137, v138, v134
	v_fma_f32 v133, -v133, v137, v135
	v_div_fmas_f32 v133, v133, v134, v137
	v_lshl_add_u32 v134, s46, 8, v1
	v_ashrrev_i32_e32 v135, 31, v134
	v_div_fixup_f32 v137, v133, v132, 1.0
	v_lshlrev_b64 v[132:133], 15, v[134:135]
	v_lshl_add_u64 v[132:133], s[22:23], 0, v[132:133]
	v_lshlrev_b64 v[138:139], 1, v[162:163]
	v_lshl_add_u64 v[132:133], v[132:133], 0, v[138:139]
	global_store_dwordx4 v[132:133], v[124:127], off
	s_nop 1
	v_pk_mul_f32 v[124:125], v[114:115], v[136:137]
	v_pk_mul_f32 v[114:115], v[112:113], v[144:145]
	v_cvt_pk_bf16_f32 v112, v120, v121
	v_cvt_pk_bf16_f32 v113, v122, v123
	s_nop 0
	v_cvt_pk_bf16_f32 v114, v114, v115
	v_cvt_pk_bf16_f32 v115, v124, v125
	global_store_dwordx4 v[132:133], v[112:115], off offset:256
	s_nop 1
	v_or_b32_e32 v112, 16, v134
	v_ashrrev_i32_e32 v113, 31, v112
	v_lshlrev_b64 v[112:113], 15, v[112:113]
	v_lshl_add_u64 v[112:113], s[22:23], 0, v[112:113]
	v_lshl_add_u64 v[112:113], v[112:113], 0, v[138:139]
	v_pk_mul_f32 v[114:115], v[118:119], v[160:161]
	v_pk_mul_f32 v[118:119], v[110:111], v[166:167]
	v_pk_mul_f32 v[110:111], v[108:109], v[164:165]
	v_cvt_pk_bf16_f32 v108, v116, v117
	v_cvt_pk_bf16_f32 v109, v114, v115
	s_nop 0
	v_cvt_pk_bf16_f32 v110, v110, v111
	v_cvt_pk_bf16_f32 v111, v118, v119
	global_store_dwordx4 v[112:113], v[108:111], off
	s_nop 1
	v_pk_mul_f32 v[108:109], v[98:99], v[136:137]
	v_pk_mul_f32 v[98:99], v[96:97], v[144:145]
	v_cvt_pk_bf16_f32 v96, v104, v105
	v_cvt_pk_bf16_f32 v97, v106, v107
	s_nop 0
	v_cvt_pk_bf16_f32 v98, v98, v99
	v_cvt_pk_bf16_f32 v99, v108, v109
	global_store_dwordx4 v[112:113], v[96:99], off offset:256
	s_nop 1
	v_or_b32_e32 v96, 32, v134
	v_ashrrev_i32_e32 v97, 31, v96
	v_lshlrev_b64 v[96:97], 15, v[96:97]
	v_lshl_add_u64 v[96:97], s[22:23], 0, v[96:97]
	v_lshl_add_u64 v[96:97], v[96:97], 0, v[138:139]
	v_pk_mul_f32 v[98:99], v[102:103], v[160:161]
	v_pk_mul_f32 v[102:103], v[94:95], v[166:167]
	v_pk_mul_f32 v[94:95], v[92:93], v[164:165]
	v_cvt_pk_bf16_f32 v92, v100, v101
	v_cvt_pk_bf16_f32 v93, v98, v99
	s_nop 0
	v_cvt_pk_bf16_f32 v94, v94, v95
	v_cvt_pk_bf16_f32 v95, v102, v103
	global_store_dwordx4 v[96:97], v[92:95], off
	s_nop 1
	v_pk_mul_f32 v[92:93], v[82:83], v[136:137]
	v_pk_mul_f32 v[82:83], v[80:81], v[144:145]
	v_cvt_pk_bf16_f32 v80, v88, v89
	v_cvt_pk_bf16_f32 v81, v90, v91
	s_nop 0
	v_cvt_pk_bf16_f32 v82, v82, v83
	v_cvt_pk_bf16_f32 v83, v92, v93
	global_store_dwordx4 v[96:97], v[80:83], off offset:256
	s_nop 1
	v_or_b32_e32 v80, 48, v134
	v_ashrrev_i32_e32 v81, 31, v80
	v_lshlrev_b64 v[80:81], 15, v[80:81]
	v_lshl_add_u64 v[80:81], s[22:23], 0, v[80:81]
	v_lshl_add_u64 v[80:81], v[80:81], 0, v[138:139]
	v_pk_mul_f32 v[82:83], v[86:87], v[160:161]
	v_pk_mul_f32 v[86:87], v[78:79], v[166:167]
	v_pk_mul_f32 v[78:79], v[76:77], v[164:165]
	v_cvt_pk_bf16_f32 v76, v84, v85
	v_cvt_pk_bf16_f32 v77, v82, v83
	s_nop 0
	v_cvt_pk_bf16_f32 v78, v78, v79
	v_cvt_pk_bf16_f32 v79, v86, v87
	global_store_dwordx4 v[80:81], v[76:79], off
	s_nop 1
	v_pk_mul_f32 v[76:77], v[70:71], v[136:137]
	v_pk_mul_f32 v[70:71], v[68:69], v[144:145]
	v_cvt_pk_bf16_f32 v68, v72, v73
	v_cvt_pk_bf16_f32 v69, v74, v75
	s_nop 0
	v_cvt_pk_bf16_f32 v70, v70, v71
	v_cvt_pk_bf16_f32 v71, v76, v77
	global_store_dwordx4 v[80:81], v[68:71], off offset:256
	s_nop 1
	v_lshl_add_u64 v[68:69], v[132:133], 0, s[4:5]
	s_mov_b32 s4, 0x400000
	v_pk_mul_f32 v[70:71], v[62:63], v[166:167]
	v_pk_mul_f32 v[62:63], v[60:61], v[164:165]
	v_cvt_pk_bf16_f32 v60, v64, v65
	v_add_co_u32_e32 v64, vcc, s4, v132
	v_cvt_pk_bf16_f32 v61, v66, v67
	v_cvt_pk_bf16_f32 v62, v62, v63
	v_cvt_pk_bf16_f32 v63, v70, v71
	s_mov_b64 s[4:5], 0x480000
	s_nop 0
	v_addc_co_u32_e32 v65, vcc, 0, v133, vcc
	global_store_dwordx4 v[64:65], v[60:63], off
	s_nop 1
	v_pk_mul_f32 v[60:61], v[50:51], v[136:137]
	v_pk_mul_f32 v[50:51], v[48:49], v[144:145]
	v_cvt_pk_bf16_f32 v48, v56, v57
	v_cvt_pk_bf16_f32 v49, v58, v59
	s_nop 0
	v_cvt_pk_bf16_f32 v50, v50, v51
	v_cvt_pk_bf16_f32 v51, v60, v61
	global_store_dwordx4 v[68:69], v[48:51], off offset:256
	s_nop 1
	v_lshl_add_u64 v[48:49], v[132:133], 0, s[4:5]
	v_pk_mul_f32 v[50:51], v[54:55], v[160:161]
	s_mov_b32 s4, 0x480000
	v_pk_mul_f32 v[54:55], v[46:47], v[166:167]
	v_pk_mul_f32 v[46:47], v[44:45], v[164:165]
	v_cvt_pk_bf16_f32 v44, v52, v53
	v_cvt_pk_bf16_f32 v45, v50, v51
	v_add_co_u32_e32 v50, vcc, s4, v132
	v_cvt_pk_bf16_f32 v46, v46, v47
	v_cvt_pk_bf16_f32 v47, v54, v55
	s_mov_b64 s[4:5], 0x500000
	s_nop 0
	v_addc_co_u32_e32 v51, vcc, 0, v133, vcc
	global_store_dwordx4 v[50:51], v[44:47], off
	s_nop 1
	v_pk_mul_f32 v[44:45], v[34:35], v[136:137]
	v_pk_mul_f32 v[34:35], v[32:33], v[144:145]
	v_cvt_pk_bf16_f32 v32, v40, v41
	v_cvt_pk_bf16_f32 v33, v42, v43
	s_nop 0
	v_cvt_pk_bf16_f32 v34, v34, v35
	v_cvt_pk_bf16_f32 v35, v44, v45
	global_store_dwordx4 v[48:49], v[32:35], off offset:256
	s_nop 1
	v_lshl_add_u64 v[32:33], v[132:133], 0, s[4:5]
	v_pk_mul_f32 v[34:35], v[38:39], v[160:161]
	s_mov_b32 s4, 0x500000
	v_pk_mul_f32 v[38:39], v[30:31], v[166:167]
	v_pk_mul_f32 v[30:31], v[28:29], v[164:165]
	v_cvt_pk_bf16_f32 v28, v36, v37
	v_cvt_pk_bf16_f32 v29, v34, v35
	v_add_co_u32_e32 v34, vcc, s4, v132
	v_cvt_pk_bf16_f32 v30, v30, v31
	v_cvt_pk_bf16_f32 v31, v38, v39
	s_mov_b64 s[4:5], 0x580000
	s_nop 0
	v_addc_co_u32_e32 v35, vcc, 0, v133, vcc
	global_store_dwordx4 v[34:35], v[28:31], off
	s_nop 1
	v_pk_mul_f32 v[28:29], v[18:19], v[136:137]
	v_pk_mul_f32 v[18:19], v[16:17], v[144:145]
	v_cvt_pk_bf16_f32 v16, v24, v25
	v_cvt_pk_bf16_f32 v17, v26, v27
	s_nop 0
	v_cvt_pk_bf16_f32 v18, v18, v19
	v_cvt_pk_bf16_f32 v19, v28, v29
	global_store_dwordx4 v[32:33], v[16:19], off offset:256
	s_nop 1
	v_lshl_add_u64 v[16:17], v[132:133], 0, s[4:5]
	v_pk_mul_f32 v[18:19], v[22:23], v[160:161]
	s_mov_b32 s4, 0x580000
	v_pk_mul_f32 v[22:23], v[14:15], v[166:167]
	v_pk_mul_f32 v[14:15], v[12:13], v[164:165]
	v_cvt_pk_bf16_f32 v12, v20, v21
	v_cvt_pk_bf16_f32 v13, v18, v19
	v_add_co_u32_e32 v18, vcc, s4, v132
	v_cvt_pk_bf16_f32 v14, v14, v15
	v_cvt_pk_bf16_f32 v15, v22, v23
	s_mov_b64 s[4:5], -1
	s_nop 0
	v_addc_co_u32_e32 v19, vcc, 0, v133, vcc
	global_store_dwordx4 v[18:19], v[12:15], off
	s_andn2_b64 vcc, exec, s[28:29]
	s_nop 0
	v_pk_mul_f32 v[12:13], v[6:7], v[136:137]
	v_pk_mul_f32 v[6:7], v[4:5], v[144:145]
	v_cvt_pk_bf16_f32 v4, v8, v9
	v_cvt_pk_bf16_f32 v5, v10, v11
	s_nop 0
	v_cvt_pk_bf16_f32 v6, v6, v7
	v_cvt_pk_bf16_f32 v7, v12, v13
	global_store_dwordx4 v[16:17], v[4:7], off offset:256
	s_cbranch_vccnz .LBB0_205
	s_andn2_b64 vcc, exec, s[24:25]
	s_cbranch_vccnz .LBB0_204
	s_barrier
	s_branch .LBB0_204
